# prompt-attention unit prologue: fourth staged chunk's dead normalisation removed as well
# speedup vs baseline: 1.0067x; 1.0034x over previous
.LBB0_857:
	s_or_b64 exec, exec, s[4:5]
	v_xor_b32_e32 v17, 1, v1
	v_cmp_lt_i32_e32 vcc, v17, v242
	s_nop 1
	v_cndmask_b32_e32 v17, v1, v17, vcc
	v_lshlrev_b32_e32 v196, 2, v17
	v_xor_b32_e32 v49, 2, v1
	v_cmp_lt_i32_e32 vcc, v49, v242
	s_nop 1
	v_cndmask_b32_e32 v49, v1, v49, vcc
	v_lshlrev_b32_e32 v197, 2, v49
	v_xor_b32_e32 v49, 4, v1
	v_cmp_lt_i32_e32 vcc, v49, v242
	s_nop 1
	v_cndmask_b32_e32 v49, v1, v49, vcc
	v_lshlrev_b32_e32 v198, 2, v49
	s_waitcnt vmcnt(0)
	v_lshlrev_b32_e32 v20, 2, v166
	v_and_b32_e32 v20, 12, v20
	v_bfe_u32 v21, v166, 2, 2
	v_bitop3_b32 v20, v20, v45, v21 bitop3:0x36
	v_lshlrev_b32_e32 v199, 8, v166
	v_lshlrev_b32_e32 v201, 4, v20
	v_add3_u32 v20, 0, v201, v199
	ds_write_b128 v20, v[116:119]
	v_lshlrev_b32_e32 v17, 2, v168
	v_and_b32_e32 v17, 12, v17
	v_bfe_u32 v22, v168, 2, 2
	v_bitop3_b32 v17, v17, v45, v22 bitop3:0x36
	v_lshlrev_b32_e32 v202, 8, v168
	v_lshlrev_b32_e32 v203, 4, v17
	v_add3_u32 v17, 0, v203, v202
	ds_write_b128 v17, v[120:123]
	v_lshlrev_b32_e32 v20, 2, v170
	v_and_b32_e32 v20, 12, v20
	v_bfe_u32 v21, v170, 2, 2
	v_bitop3_b32 v20, v20, v45, v21 bitop3:0x36
	v_lshlrev_b32_e32 v204, 8, v170
	v_lshlrev_b32_e32 v205, 4, v20
	v_add3_u32 v20, 0, v205, v204
	ds_write_b128 v20, v[124:127]
	s_sub_i32 s21, 0, s8
	s_lshl_b32 s12, s9, 7
	v_add_f32_e32 v44, v44, v48
	v_mul_f32_e32 v48, 0x4f800000, v44
	v_cmp_gt_f32_e32 vcc, s11, v44
	v_add_f32_e32 v46, v46, v47
	v_and_b32_e32 v25, 63, v59
	v_cndmask_b32_e32 v44, v44, v48, vcc
	v_sqrt_f32_e32 v48, v44
	v_lshlrev_b32_e32 v218, 8, v172
	s_lshl_b32 s25, s21, 1
	s_movk_i32 s4, 0x50
	v_add_u32_e32 v47, -1, v48
	v_fma_f32 v65, -v47, v48, v44
	v_cmp_ge_f32_e64 s[8:9], 0, v65
	v_add_u32_e32 v65, 1, v48
	v_readlane_b32 s36, v254, 28
	v_cndmask_b32_e64 v47, v48, v47, s[8:9]
	v_fma_f32 v48, -v65, v48, v44
	v_cmp_lt_f32_e64 s[8:9], 0, v48
	v_lshrrev_b32_e32 v61, 16, v38
	s_add_i32 s25, s25, 16
	v_cndmask_b32_e64 v47, v47, v65, s[8:9]
	v_mul_f32_e32 v48, 0x37800000, v47
	v_cndmask_b32_e32 v47, v47, v48, vcc
	v_mul_f32_e32 v48, 0x4f800000, v46
	v_cmp_gt_f32_e32 vcc, s11, v46
	v_cmp_class_f32_e64 s[8:9], v44, v192
	s_bitset1_b32 s18, 7
	v_cndmask_b32_e32 v46, v46, v48, vcc
	v_sqrt_f32_e32 v48, v46
	v_cndmask_b32_e64 v44, v47, v44, s[8:9]
	v_mul_f32_e32 v44, 0x41000000, v44
	s_or_b32 s26, s24, 31
	v_add_u32_e32 v47, -1, v48
	v_fma_f32 v65, -v47, v48, v46
	v_cmp_ge_f32_e64 s[8:9], 0, v65
	v_add_u32_e32 v65, 1, v48
	v_readlane_b32 s48, v254, 40
	v_cndmask_b32_e64 v47, v48, v47, s[8:9]
	v_fma_f32 v48, -v65, v48, v46
	v_cmp_lt_f32_e64 s[8:9], 0, v48
	v_perm_b32 v156, v61, v38, s22
	v_readlane_b32 s37, v254, 29
	v_cndmask_b32_e64 v47, v47, v65, s[8:9]
	v_mul_f32_e32 v48, 0x37800000, v47
	v_cndmask_b32_e32 v47, v47, v48, vcc
	v_cmp_class_f32_e32 vcc, v46, v192
	v_bfe_u32 v48, v59, 1, 1
	v_readlane_b32 s38, v254, 30
	v_cndmask_b32_e32 v46, v47, v46, vcc
	v_mul_f32_e32 v46, 0x40b504f3, v46
	v_mul_f32_e32 v15, v15, v46
	v_fmac_f32_e32 v15, v14, v44
	v_lshlrev_b32_e32 v14, 2, v55
	v_and_b32_e32 v14, 12, v14
	v_bfe_u32 v44, v59, 2, 2
	v_bitop3_b32 v46, v14, v51, v44 bitop3:0x36
	v_lshlrev_b32_e32 v207, 4, v46
	v_or_b32_e32 v46, 2, v51
	v_bitop3_b32 v46, v14, v46, v44 bitop3:0x36
	v_lshlrev_b32_e32 v208, 4, v46
	v_or_b32_e32 v46, 4, v51
	v_bitop3_b32 v46, v14, v46, v44 bitop3:0x36
	v_lshlrev_b32_e32 v209, 4, v46
	v_or_b32_e32 v46, 6, v51
	v_bitop3_b32 v14, v14, v46, v44 bitop3:0x36
	v_lshlrev_b32_e32 v210, 4, v14
	v_lshrrev_b32_e32 v14, 3, v25
	v_fmamk_f32 v46, v15, 0x3f828f5c, v193
	v_and_b32_e32 v15, 4, v14
	v_or_b32_e32 v47, v15, v44
	v_and_or_b32 v14, v14, 2, v48
	v_lshlrev_b32_e32 v25, 3, v25
	v_or_b32_e32 v15, 8, v15
	v_or_b32_e32 v48, 8, v14
	v_lshlrev_b32_e32 v211, 8, v47
	v_and_b32_e32 v47, 12, v59
	v_and_b32_e32 v213, 8, v25
	v_or_b32_e32 v25, v15, v44
	v_lshrrev_b32_e32 v15, 2, v15
	v_or_b32_e32 v59, v51, v47
	v_lshlrev_b32_e32 v214, 8, v25
	v_bitop3_b32 v25, v15, v48, v47 bitop3:0x36
	v_bitop3_b32 v65, v14, v59, 8 bitop3:0x36
	v_lshlrev_b32_e32 v215, 4, v25
	v_or_b32_e32 v25, 12, v14
	v_bitop3_b32 v14, v14, v59, 12 bitop3:0x36
	v_lshlrev_b32_e32 v216, 4, v14
	v_bitop3_b32 v14, v15, v25, v47 bitop3:0x36
	v_lshlrev_b32_e32 v217, 4, v14
	v_lshlrev_b32_e32 v8, 2, v172
	v_and_b32_e32 v8, 12, v8
	v_bfe_u32 v9, v172, 2, 2
	v_bitop3_b32 v8, v8, v45, v9 bitop3:0x36
	v_lshlrev_b32_e32 v219, 4, v8
	v_add3_u32 v8, 0, v219, v218
	ds_write_b128 v8, v[128:131]
	v_mul_lo_u32 v4, v174, s4
	s_lshl_b32 s4, s12, 1
	v_readlane_b32 s39, v254, 31
	v_readlane_b32 s40, v254, 32
	v_readlane_b32 s41, v254, 33
	v_readlane_b32 s42, v254, 34
	v_readlane_b32 s43, v254, 35
	v_readlane_b32 s44, v254, 36
	v_readlane_b32 s45, v254, 37
	v_readlane_b32 s46, v254, 38
	v_readlane_b32 s47, v254, 39
	v_readlane_b32 s49, v254, 41
	v_readlane_b32 s50, v254, 42
	v_readlane_b32 s51, v254, 43
	s_add_u32 s4, s48, s4
	v_mov_b32_e32 v61, v3
	v_lshrrev_b32_e32 v56, 16, v13
	v_add3_u32 v220, s80, v4, v60
	s_addc_u32 s5, s49, 0
	v_lshl_add_u64 v[178:179], s[40:41], 0, v[60:61]
	v_readlane_b32 s36, v253, 40
	v_lshrrev_b32_e32 v49, 16, v30
	v_lshrrev_b32_e32 v50, 16, v31
	v_lshrrev_b32_e32 v57, 16, v36
	v_lshrrev_b32_e32 v58, 16, v37
	v_lshrrev_b32_e32 v63, 16, v40
	v_lshrrev_b32_e32 v64, 16, v41
	ds_write_b128 v220, v[132:135]
	v_mul_u32_u24_e32 v4, 0x50, v55
	v_perm_b32 v152, v56, v13, s22
	v_mov_b32_e32 v13, v3
	v_readlane_b32 s37, v253, 41
	v_mov_b32_e32 v16, v3
	v_mov_b32_e32 v17, v3
	s_waitcnt lgkmcnt(0)
	s_barrier
	v_add3_u32 v222, s80, v4, v62
	v_xor_b32_e32 v20, 0x80000000, v46
	v_perm_b32 v146, v50, v31, s22
	v_perm_b32 v145, v49, v30, s22
	v_perm_b32 v154, v58, v37, s22
	v_perm_b32 v153, v57, v36, s22
	v_perm_b32 v158, v64, v41, s22
	v_perm_b32 v157, v63, v40, s22
	v_bfi_b32 v159, s23, v39, v39
	v_bfi_b32 v139, s23, v43, v43
	v_bfi_b32 v143, s23, v42, v42
	v_lshlrev_b32_e32 v221, 2, v51
	v_lshl_add_u64 v[176:177], s[4:5], 0, v[2:3]
	v_lshl_add_u64 v[180:181], s[36:37], 0, v[12:13]
	v_mov_b32_e32 v240, 1.0
	v_mov_b32_e32 v241, 1.0
	v_mov_b32_e32 v243, 1.0
	v_mov_b32_e32 v252, 1.0
	v_mov_b32_e32 v248, 1.0
	v_mov_b32_e32 v249, 1.0
	v_mov_b32_e32 v250, 1.0
	v_mov_b32_e32 v251, 1.0
	s_mov_b64 vcc, exec
	s_and_b64 exec, exec, s[0:1]
	global_load_dwordx4 v[248:251], v[180:181], off
	global_load_dwordx2 v[240:241], v[180:181], off offset:16
	global_load_dword v243, v[180:181], off offset:24
	global_load_dword v252, v[180:181], off offset:28
	s_mov_b64 exec, vcc
	v_mov_b32_e32 v2, v3
	v_mov_b32_e32 v4, v3
	v_mov_b32_e32 v5, v3
	v_mov_b32_e32 v6, v3
	v_mov_b32_e32 v7, v3
	v_mov_b32_e32 v8, v3
	v_mov_b32_e32 v9, v3
	v_mov_b32_e32 v10, v3
	v_mov_b32_e32 v11, v3
	v_mov_b32_e32 v12, v3
	v_mov_b32_e32 v14, v3
	v_mov_b32_e32 v15, v3
	v_mov_b64_e32 v[50:51], v[16:17]
	s_waitcnt lgkmcnt(2)
	v_lshrrev_b32_e32 v26, 16, v28
	v_lshrrev_b32_e32 v52, 16, v27
	v_lshrrev_b32_e32 v53, 16, v33
	v_lshrrev_b32_e32 v54, 16, v34
	v_mov_b64_e32 v[48:49], v[14:15]
	v_mov_b64_e32 v[46:47], v[12:13]
	v_mov_b64_e32 v[44:45], v[10:11]
	v_mov_b64_e32 v[42:43], v[8:9]
	v_mov_b64_e32 v[40:41], v[6:7]
	v_mov_b64_e32 v[38:39], v[4:5]
	v_mov_b64_e32 v[36:37], v[2:3]
	v_mov_b64_e32 v[18:19], v[16:17]
	s_mov_b32 s20, 0
	v_lshlrev_b32_e32 v206, 8, v55
	v_lshlrev_b32_e32 v212, 4, v65
	v_perm_b32 v144, v26, v28, s22
	v_bfi_b32 v147, s23, v29, v29
	v_perm_b32 v150, v54, v34, s22
	v_perm_b32 v149, v53, v33, s22
	v_perm_b32 v148, v52, v27, s22
	v_bfi_b32 v151, s23, v32, v32
	v_bfi_b32 v155, s23, v35, v35
	v_mov_b32_e32 v21, v20
	v_mov_b32_e32 v22, v20
	v_mov_b32_e32 v23, v20
	v_mov_b32_e32 v24, v20
	v_mov_b32_e32 v25, v20
	v_mov_b32_e32 v26, v20
	v_mov_b32_e32 v27, v20
	v_mov_b32_e32 v28, v20
	v_mov_b32_e32 v29, v20
	v_mov_b32_e32 v30, v20
	v_mov_b32_e32 v31, v20
	v_mov_b32_e32 v32, v20
	v_mov_b32_e32 v33, v20
	v_mov_b32_e32 v34, v20
	v_mov_b32_e32 v35, v20
	v_mov_b32_e32 v223, 0
	s_movk_i32 s27, 0x7f
	v_mov_b64_e32 v[16:17], v[14:15]
	v_mov_b64_e32 v[14:15], v[12:13]
	v_mov_b64_e32 v[12:13], v[10:11]
	v_mov_b64_e32 v[10:11], v[8:9]
	v_mov_b64_e32 v[8:9], v[6:7]
	v_mov_b64_e32 v[6:7], v[4:5]
	v_mov_b64_e32 v[4:5], v[2:3]
	v_readlane_b32 s38, v253, 42
	v_readlane_b32 s39, v253, 43
	v_readlane_b32 s40, v253, 44
	v_readlane_b32 s41, v253, 45
	v_readlane_b32 s42, v253, 46
	v_readlane_b32 s43, v253, 47
	v_readlane_b32 s44, v253, 48
	v_readlane_b32 s45, v253, 49
	v_readlane_b32 s46, v253, 50
	v_readlane_b32 s47, v253, 51
	v_readlane_b32 s48, v253, 52
	v_readlane_b32 s49, v253, 53
	v_readlane_b32 s50, v253, 54
	v_readlane_b32 s51, v253, 55
